# XCD-aware tile remap also for the gate/up GEMM (4 row-blocks x 16 col tiles per XCD per wave) and the even in-proj GEMM (8x8 tile patch per XCD per wave)
# speedup vs baseline: 1.0038x; 1.0038x over previous
; DI int bid_l() { int t = blockIdx.x; asm volatile("" : "+s"(t)); return t; }
; DI f32x16 zero16() { f32x16 z; for (int i = 0; i < 16; ++i) z[i] = 0.f; return z; }
; template <int MF, int BK, class Epi>
; DI void gemm_phase_t(char* lds, const GemmDesc g, const Epi epi) {
;     ...
;   for (int t = bid_l(); t < ntiles; t += gridDim.x) {
;     const int tn = t % ntn, tm = t / ntn;
;     const int m0 = tm * BM, n0 = tn * 128;
;     const u16* Ap = g.A + (size_t)(m0 + lr) * g.lda + lc * 8;
;     const u16* Bp = g.Bt + (size_t)(n0 + lr) * g.ldb + lc * 8;
;     u32x4 ra[APT], rb[BPT];
; #pragma unroll
;     for (int j = 0; j < APT; ++j) ra[j] = *(const u32x4*)(Ap + (size_t)j * RSTEP * g.lda);
; #pragma unroll
;     for (int j = 0; j < BPT; ++j) rb[j] = *(const u32x4*)(Bp + (size_t)j * RSTEP * g.ldb);
; #pragma unroll
;     for (int j = 0; j < APT; ++j) *(u32x4*)(sbase + (lr + RSTEP * j) * LS + lc * 8) = ra[j];
; #pragma unroll
;     for (int j = 0; j < BPT; ++j) *(u32x4*)(sbase + BM * LS + (lr + RSTEP * j) * LS + lc * 8) = rb[j];
;     if (nk > 1) {
; #pragma unroll
;       for (int j = 0; j < APT; ++j) ra[j] = *(const u32x4*)(Ap + (size_t)j * RSTEP * g.lda + BK);
; #pragma unroll
;       for (int j = 0; j < BPT; ++j) rb[j] = *(const u32x4*)(Bp + (size_t)j * RSTEP * g.ldb + BK);
;     }
;     f32x16 acc[MF][2];
; #pragma unroll
;     for (int i = 0; i < MF; ++i)
; #pragma unroll
;       for (int j = 0; j < 2; ++j) acc[i][j] = zero16();
.LBB0_287:
	s_mov_b32 s101, s7
	v_readlane_b32 s4, v252, 40
	s_cmpk_lg_i32 s4, 0x200
	s_cbranch_scc1 .Lnomap_gu
	s_cmpk_lg_i32 s6, 0x580
	s_cbranch_scc1 .Lnomap_gu
	s_lshr_b32 s4, s7, 9
	s_lshl_b32 s4, s4, 6
	s_bfe_u32 s5, s7, 0x60003
	s_add_i32 s4, s4, s5
	s_and_b32 s5, s7, 7
	s_lshl_b32 s5, s5, 2
	s_and_b32 s8, s4, 3
	s_add_i32 s5, s5, s8
	s_mul_i32 s5, s5, 44
	s_lshr_b32 s4, s4, 2
	s_add_i32 s101, s5, s4
.Lnomap_gu:
	s_mul_hi_i32 s4, s101, 0x2e8ba2e9
	s_lshr_b32 s5, s4, 31
	s_ashr_i32 s4, s4, 3
	s_add_i32 s4, s4, s5
	s_lshl_b32 s8, s4, 8
	v_add_u32_e32 v4, s8, v2
	s_mul_i32 s5, s4, 44
	v_ashrrev_i32_e32 v5, 31, v4
	s_sub_i32 s5, s101, s5
	v_lshlrev_b64 v[68:69], 11, v[4:5]
	s_lshl_b32 s9, s5, 7
	v_lshl_add_u64 v[70:71], v[158:159], 0, v[68:69]
	s_mov_b32 s5, 0x20000
	v_add_co_u32_e32 v74, vcc, s5, v70
	s_mov_b32 s4, 0x40000
	s_nop 0
	v_addc_co_u32_e32 v75, vcc, 0, v71, vcc
	v_add_u32_e32 v4, s9, v2
	v_add_co_u32_e32 v76, vcc, s4, v70
	v_ashrrev_i32_e32 v5, 31, v4
	s_nop 0
	v_addc_co_u32_e32 v77, vcc, 0, v71, vcc
	s_mov_b32 s4, 0x60000
	v_lshlrev_b64 v[72:73], 11, v[4:5]
	v_add_co_u32_e32 v78, vcc, s4, v70
	v_lshl_add_u64 v[80:81], v[162:163], 0, v[72:73]
	s_nop 0
	v_addc_co_u32_e32 v79, vcc, 0, v71, vcc
	v_add_co_u32_e32 v82, vcc, s5, v80
	v_addc_co_u32_e32 v83, vcc, 0, v81, vcc
	s_mov_b32 m0, s98
	s_nop 0
	global_load_lds_dwordx4 v[70:71], off
	s_add_i32 m0, s98, 0x1000
	s_nop 0
	global_load_lds_dwordx4 v[74:75], off
	s_add_i32 m0, s98, 0x2000
	s_nop 0
	global_load_lds_dwordx4 v[76:77], off
	s_add_i32 m0, s98, 0x3000
	s_nop 0
	global_load_lds_dwordx4 v[78:79], off
	s_add_i32 m0, s98, 0x4000
	s_nop 0
	global_load_lds_dwordx4 v[80:81], off
	s_add_i32 m0, s98, 0x5000
	s_nop 0
	global_load_lds_dwordx4 v[82:83], off
	s_add_i32 m0, s99, 0xffffffc0
	s_nop 0
	global_load_lds_dwordx4 v[70:71], off offset:64
	s_add_i32 m0, s99, 0xfc0
	s_nop 0
	global_load_lds_dwordx4 v[74:75], off offset:64
	s_add_i32 m0, s99, 0x1fc0
	s_nop 0
	global_load_lds_dwordx4 v[76:77], off offset:64
	s_add_i32 m0, s99, 0x2fc0
	s_nop 0
	global_load_lds_dwordx4 v[78:79], off offset:64
	s_add_i32 m0, s99, 0x3fc0
	s_nop 0
	global_load_lds_dwordx4 v[80:81], off offset:64
	s_add_i32 m0, s99, 0x4fc0
	s_nop 0
	global_load_lds_dwordx4 v[82:83], off offset:64
	v_mov_b32_e32 v4, 0
	s_mov_b64 s[4:5], 0
	v_mov_b32_e32 v5, v4
	v_mov_b32_e32 v6, v4
	v_mov_b32_e32 v7, v4
	v_mov_b32_e32 v8, v4
	v_mov_b32_e32 v9, v4
	v_mov_b32_e32 v10, v4
	v_mov_b32_e32 v11, v4
	v_mov_b32_e32 v12, v4
	v_mov_b32_e32 v13, v4
	v_mov_b32_e32 v14, v4
	v_mov_b32_e32 v15, v4
	v_mov_b32_e32 v16, v4
	v_mov_b32_e32 v17, v4
	v_mov_b32_e32 v18, v4
	v_mov_b32_e32 v19, v4
	v_mov_b32_e32 v20, v4
	v_mov_b32_e32 v21, v4
	v_mov_b32_e32 v22, v4
	v_mov_b32_e32 v23, v4
	v_mov_b32_e32 v24, v4
	v_mov_b32_e32 v25, v4
	v_mov_b32_e32 v26, v4
	v_mov_b32_e32 v27, v4
	v_mov_b32_e32 v28, v4
	v_mov_b32_e32 v29, v4
	v_mov_b32_e32 v30, v4
	v_mov_b32_e32 v31, v4
	v_mov_b32_e32 v32, v4
	v_mov_b32_e32 v33, v4
	v_mov_b32_e32 v34, v4
	v_mov_b32_e32 v35, v4
	v_mov_b32_e32 v36, v4
	v_mov_b32_e32 v37, v4
	v_mov_b32_e32 v38, v4
	v_mov_b32_e32 v39, v4
	v_mov_b32_e32 v40, v4
	v_mov_b32_e32 v41, v4
	v_mov_b32_e32 v42, v4
	v_lshl_add_u64 v[164:165], v[156:157], 0, v[68:69]
	v_lshl_add_u64 v[168:169], v[160:161], 0, v[72:73]
	v_mov_b32_e32 v43, v4
	v_mov_b32_e32 v68, v4
	v_mov_b32_e32 v69, v4
	v_mov_b32_e32 v70, v4
	v_mov_b32_e32 v71, v4
	v_mov_b32_e32 v72, v4
	v_mov_b32_e32 v44, v4
	v_mov_b32_e32 v45, v4
	v_mov_b32_e32 v46, v4
	v_mov_b32_e32 v47, v4
	v_mov_b32_e32 v48, v4
	v_mov_b32_e32 v49, v4
	v_mov_b32_e32 v50, v4
	v_mov_b32_e32 v51, v4
	v_mov_b32_e32 v52, v4
	v_mov_b32_e32 v53, v4
	v_mov_b32_e32 v54, v4
	v_mov_b32_e32 v55, v4
	v_mov_b32_e32 v56, v4
	v_mov_b32_e32 v57, v4
	v_mov_b32_e32 v58, v4
	v_mov_b32_e32 v59, v4
	v_mov_b32_e32 v60, v4
	v_mov_b32_e32 v61, v4
	v_mov_b32_e32 v62, v4
	v_mov_b32_e32 v63, v4
	v_mov_b32_e32 v64, v4
	v_mov_b32_e32 v65, v4
	v_mov_b32_e32 v66, v4
	v_mov_b32_e32 v67, v4
	v_mov_b32_e32 v73, v4
	v_mov_b32_e32 v74, v4
	v_mov_b32_e32 v75, v4
	v_mov_b32_e32 v76, v4
	v_mov_b32_e32 v77, v4
	v_mov_b32_e32 v78, v4
	v_mov_b32_e32 v79, v4
	v_mov_b32_e32 v80, v4
	v_mov_b32_e32 v81, v4
	v_mov_b32_e32 v82, v4
	v_mov_b32_e32 v83, v4
	v_mov_b32_e32 v84, v4
	v_mov_b32_e32 v85, v4
	v_mov_b32_e32 v86, v4
	v_mov_b32_e32 v87, v4
	v_mov_b32_e32 v88, v4
	v_mov_b32_e32 v89, v4
	v_mov_b32_e32 v90, v4
	v_mov_b32_e32 v91, v4
	v_mov_b32_e32 v92, v4
	v_mov_b32_e32 v93, v4
	v_mov_b32_e32 v94, v4
	v_mov_b32_e32 v95, v4
	v_mov_b32_e32 v96, v4
	v_mov_b32_e32 v97, v4
	v_mov_b32_e32 v98, v4
	v_mov_b32_e32 v99, v4
	v_mov_b32_e32 v100, v4
	v_mov_b32_e32 v101, v4
	v_mov_b32_e32 v102, v4
	v_mov_b32_e32 v103, v4
	v_mov_b32_e32 v104, v4
	v_mov_b32_e32 v105, v4
	v_mov_b32_e32 v106, v4
	v_mov_b32_e32 v107, v4
	v_mov_b32_e32 v108, v4
	v_mov_b32_e32 v109, v4
	v_mov_b32_e32 v110, v4
	v_mov_b32_e32 v111, v4
	v_mov_b32_e32 v112, v4
	v_mov_b32_e32 v113, v4
	v_mov_b32_e32 v114, v4
	v_mov_b32_e32 v115, v4
	v_mov_b32_e32 v116, v4
	v_mov_b32_e32 v117, v4
	v_mov_b32_e32 v118, v4
	v_mov_b32_e32 v119, v4
	v_mov_b32_e32 v120, v4
	v_mov_b32_e32 v121, v4
	v_mov_b32_e32 v122, v4
	v_mov_b32_e32 v123, v4
	v_mov_b32_e32 v124, v4
	v_mov_b32_e32 v125, v4
	v_mov_b32_e32 v126, v4
	v_mov_b32_e32 v127, v4
	v_mov_b32_e32 v128, v4
	v_mov_b32_e32 v129, v4
	v_mov_b32_e32 v130, v4
	v_mov_b32_e32 v131, v4
	s_mov_b32 s11, 0x147ac000
	s_mov_b32 s12, 0x147cc000
	s_mov_b32 s13, 0x147ec000
	s_mov_b32 s14, 0x1480c000

; DI int bid_l() { int t = blockIdx.x; asm volatile("" : "+s"(t)); return t; }
; DI f32x16 zero16() { f32x16 z; for (int i = 0; i < 16; ++i) z[i] = 0.f; return z; }
; template <int MF, int BK, class Epi>
; DI void gemm_phase_t(char* lds, const GemmDesc g, const Epi epi) {
;     ...
;   for (int t = bid_l(); t < ntiles; t += gridDim.x) {
;     const int tn = t % ntn, tm = t / ntn;
;     const int m0 = tm * BM, n0 = tn * 128;
;     const u16* Ap = g.A + (size_t)(m0 + lr) * g.lda + lc * 8;
;     const u16* Bp = g.Bt + (size_t)(n0 + lr) * g.ldb + lc * 8;
;     u32x4 ra[APT], rb[BPT];
; #pragma unroll
;     for (int j = 0; j < APT; ++j) ra[j] = *(const u32x4*)(Ap + (size_t)j * RSTEP * g.lda);
; #pragma unroll
;     for (int j = 0; j < BPT; ++j) rb[j] = *(const u32x4*)(Bp + (size_t)j * RSTEP * g.ldb);
; #pragma unroll
;     for (int j = 0; j < APT; ++j) *(u32x4*)(sbase + (lr + RSTEP * j) * LS + lc * 8) = ra[j];
; #pragma unroll
;     for (int j = 0; j < BPT; ++j) *(u32x4*)(sbase + BM * LS + (lr + RSTEP * j) * LS + lc * 8) = rb[j];
;     if (nk > 1) {
; #pragma unroll
;       for (int j = 0; j < APT; ++j) ra[j] = *(const u32x4*)(Ap + (size_t)j * RSTEP * g.lda + BK);
; #pragma unroll
;       for (int j = 0; j < BPT; ++j) rb[j] = *(const u32x4*)(Bp + (size_t)j * RSTEP * g.ldb + BK);
;     }
;     f32x16 acc[MF][2];
; #pragma unroll
;     for (int i = 0; i < MF; ++i)
; #pragma unroll
;       for (int j = 0; j < 2; ++j) acc[i][j] = zero16();
.LBB0_953:
	s_mov_b32 s101, s10
	v_readlane_b32 s0, v252, 40
	s_cmpk_lg_i32 s0, 0x200
	s_cbranch_scc1 .Lnomap_ie
	s_bfe_u32 s0, s10, 0x60003
	s_and_b32 s1, s10, 7
	s_lshr_b32 s2, s10, 9
	s_cmp_eq_u32 s2, 8
	s_cbranch_scc1 .Lmap_ie_tail
	s_lshl_b32 s2, s2, 4
	s_lshr_b32 s3, s1, 2
	s_lshl_b32 s3, s3, 3
	s_add_i32 s2, s2, s3
	s_lshr_b32 s3, s0, 3
	s_add_i32 s2, s2, s3
	s_and_b32 s1, s1, 3
	s_lshl_b32 s1, s1, 3
	s_and_b32 s0, s0, 7
	s_add_i32 s1, s1, s0
	s_lshl_b32 s2, s2, 5
	s_add_i32 s101, s2, s1
	s_branch .Lnomap_ie
.Lmap_ie_tail:
	s_lshr_b32 s2, s0, 2
	s_add_i32 s2, s2, 0x80
	s_lshl_b32 s2, s2, 5
	s_lshl_b32 s1, s1, 2
	s_and_b32 s0, s0, 3
	s_add_i32 s1, s1, s0
	s_add_i32 s101, s2, s1
.Lnomap_ie:
	s_ashr_i32 s0, s101, 31
	s_lshr_b32 s0, s0, 27
	s_add_i32 s0, s101, s0
	s_and_b32 s1, s0, 0x1ffffe0
	s_lshl_b32 s0, s0, 3
	s_and_b32 s2, s0, 0xffffff00
	v_add_u32_e32 v4, s2, v2
	v_ashrrev_i32_e32 v5, 31, v4
	s_sub_i32 s1, s101, s1
	v_lshlrev_b64 v[68:69], 11, v[4:5]
	s_lshl_b32 s3, s1, 7
	v_lshl_add_u64 v[70:71], v[158:159], 0, v[68:69]
	s_mov_b32 s1, 0x20000
	v_add_co_u32_e32 v74, vcc, s1, v70
	s_mov_b32 s0, 0x40000
	s_nop 0
	v_addc_co_u32_e32 v75, vcc, 0, v71, vcc
	v_add_u32_e32 v4, s3, v2
	v_add_co_u32_e32 v76, vcc, s0, v70
	v_ashrrev_i32_e32 v5, 31, v4
	s_nop 0
	v_addc_co_u32_e32 v77, vcc, 0, v71, vcc
	s_mov_b32 s0, 0x60000
	v_lshlrev_b64 v[72:73], 11, v[4:5]
	v_add_co_u32_e32 v78, vcc, s0, v70
	v_lshl_add_u64 v[80:81], v[160:161], 0, v[72:73]
	s_nop 0
	v_addc_co_u32_e32 v79, vcc, 0, v71, vcc
	v_add_co_u32_e32 v82, vcc, s1, v80
	v_addc_co_u32_e32 v83, vcc, 0, v81, vcc
	s_mov_b32 m0, s98
	s_nop 0
	global_load_lds_dwordx4 v[70:71], off
	s_add_i32 m0, s98, 0x1000
	s_nop 0
	global_load_lds_dwordx4 v[74:75], off
	s_add_i32 m0, s98, 0x2000
	s_nop 0
	global_load_lds_dwordx4 v[76:77], off
	s_add_i32 m0, s98, 0x3000
	s_nop 0
	global_load_lds_dwordx4 v[78:79], off
	s_add_i32 m0, s98, 0x4000
	s_nop 0
	global_load_lds_dwordx4 v[80:81], off
	s_add_i32 m0, s98, 0x5000
	s_nop 0
	global_load_lds_dwordx4 v[82:83], off
	s_add_i32 m0, s99, 0xffffffc0
	s_nop 0
	global_load_lds_dwordx4 v[70:71], off offset:64
	s_add_i32 m0, s99, 0xfc0
	s_nop 0
	global_load_lds_dwordx4 v[74:75], off offset:64
	s_add_i32 m0, s99, 0x1fc0
	s_nop 0
	global_load_lds_dwordx4 v[76:77], off offset:64
	s_add_i32 m0, s99, 0x2fc0
	s_nop 0
	global_load_lds_dwordx4 v[78:79], off offset:64
	s_add_i32 m0, s99, 0x3fc0
	s_nop 0
	global_load_lds_dwordx4 v[80:81], off offset:64
	s_add_i32 m0, s99, 0x4fc0
	s_nop 0
	global_load_lds_dwordx4 v[82:83], off offset:64
	v_mov_b32_e32 v4, 0
	s_mov_b64 s[0:1], 0
	v_mov_b32_e32 v5, v4
	v_mov_b32_e32 v6, v4
	v_mov_b32_e32 v7, v4
	v_mov_b32_e32 v8, v4
	v_mov_b32_e32 v9, v4
	v_mov_b32_e32 v10, v4
	v_mov_b32_e32 v11, v4
	v_mov_b32_e32 v12, v4
	v_mov_b32_e32 v13, v4
	v_mov_b32_e32 v14, v4
	v_mov_b32_e32 v15, v4
	v_mov_b32_e32 v16, v4
	s_waitcnt lgkmcnt(0)
	v_mov_b32_e32 v17, v4
	v_mov_b32_e32 v18, v4
	v_mov_b32_e32 v19, v4
	v_mov_b32_e32 v20, v4
	v_mov_b32_e32 v21, v4
	v_mov_b32_e32 v22, v4
	v_mov_b32_e32 v23, v4
	v_mov_b32_e32 v24, v4
	v_mov_b32_e32 v25, v4
	v_mov_b32_e32 v26, v4
	v_mov_b32_e32 v27, v4
	v_mov_b32_e32 v28, v4
	v_mov_b32_e32 v29, v4
	v_mov_b32_e32 v30, v4
	v_mov_b32_e32 v31, v4
	v_mov_b32_e32 v32, v4
	v_mov_b32_e32 v33, v4
	v_mov_b32_e32 v34, v4
	v_mov_b32_e32 v35, v4
	v_mov_b32_e32 v36, v4
	v_mov_b32_e32 v37, v4
	v_mov_b32_e32 v38, v4
	v_mov_b32_e32 v39, v4
	v_mov_b32_e32 v40, v4
	v_mov_b32_e32 v41, v4
	v_mov_b32_e32 v42, v4
	v_lshl_add_u64 v[162:163], v[156:157], 0, v[68:69]
	v_lshl_add_u64 v[164:165], v[156:157], 0, v[72:73]
	v_mov_b32_e32 v43, v4
	v_mov_b32_e32 v68, v4
	v_mov_b32_e32 v69, v4
	v_mov_b32_e32 v70, v4
	v_mov_b32_e32 v71, v4
	v_mov_b32_e32 v72, v4
	v_mov_b32_e32 v73, v4
	v_mov_b32_e32 v44, v4
	v_mov_b32_e32 v45, v4
	v_mov_b32_e32 v46, v4
	v_mov_b32_e32 v47, v4
	v_mov_b32_e32 v48, v4
	v_mov_b32_e32 v49, v4
	v_mov_b32_e32 v50, v4
	v_mov_b32_e32 v51, v4
	v_mov_b32_e32 v52, v4
	v_mov_b32_e32 v53, v4
	v_mov_b32_e32 v54, v4
	v_mov_b32_e32 v55, v4
	v_mov_b32_e32 v56, v4
	v_mov_b32_e32 v57, v4
	v_mov_b32_e32 v58, v4
	v_mov_b32_e32 v59, v4
	v_mov_b32_e32 v60, v4
	v_mov_b32_e32 v61, v4
	v_mov_b32_e32 v62, v4
	v_mov_b32_e32 v63, v4
	v_mov_b32_e32 v64, v4
	v_mov_b32_e32 v65, v4
	v_mov_b32_e32 v66, v4
	v_mov_b32_e32 v67, v4
	v_mov_b32_e32 v74, v4
	v_mov_b32_e32 v75, v4
	v_mov_b32_e32 v76, v4
	v_mov_b32_e32 v77, v4
	v_mov_b32_e32 v78, v4
	v_mov_b32_e32 v79, v4
	v_mov_b32_e32 v80, v4
	v_mov_b32_e32 v81, v4
	v_mov_b32_e32 v82, v4
	v_mov_b32_e32 v83, v4
	v_mov_b32_e32 v84, v4
	v_mov_b32_e32 v85, v4
	v_mov_b32_e32 v86, v4
	v_mov_b32_e32 v87, v4
	v_mov_b32_e32 v88, v4
	v_mov_b32_e32 v89, v4
	v_mov_b32_e32 v90, v4
	v_mov_b32_e32 v91, v4
	v_mov_b32_e32 v92, v4
	v_mov_b32_e32 v93, v4
	v_mov_b32_e32 v94, v4
	v_mov_b32_e32 v95, v4
	v_mov_b32_e32 v96, v4
	v_mov_b32_e32 v97, v4
	v_mov_b32_e32 v98, v4
	v_mov_b32_e32 v99, v4
	v_mov_b32_e32 v100, v4
	v_mov_b32_e32 v101, v4
	v_mov_b32_e32 v102, v4
	v_mov_b32_e32 v103, v4
	v_mov_b32_e32 v104, v4
	v_mov_b32_e32 v105, v4
	v_mov_b32_e32 v106, v4
	v_mov_b32_e32 v107, v4
	v_mov_b32_e32 v108, v4
	v_mov_b32_e32 v109, v4
	v_mov_b32_e32 v110, v4
	v_mov_b32_e32 v111, v4
	v_mov_b32_e32 v112, v4
	v_mov_b32_e32 v113, v4
	v_mov_b32_e32 v114, v4
	v_mov_b32_e32 v115, v4
	v_mov_b32_e32 v116, v4
	v_mov_b32_e32 v117, v4
	v_mov_b32_e32 v118, v4
	v_mov_b32_e32 v119, v4
	v_mov_b32_e32 v120, v4
	v_mov_b32_e32 v121, v4
	v_mov_b32_e32 v122, v4
	v_mov_b32_e32 v123, v4
	v_mov_b32_e32 v124, v4
	v_mov_b32_e32 v125, v4
	v_mov_b32_e32 v126, v4
	v_mov_b32_e32 v127, v4
	v_mov_b32_e32 v128, v4
	v_mov_b32_e32 v129, v4
	v_mov_b32_e32 v130, v4
	v_mov_b32_e32 v131, v4
	s_mov_b32 s5, 0x147ac000
	s_mov_b32 s11, 0x147cc000
	s_mov_b32 s12, 0x147ec000
	s_mov_b32 s13, 0x1480c000
